# prune key tiles whose total softmax mass is provably below 2^-53 (46 nats) instead of f32 underflow (88); drop entry grid.sync; relax epilogue vmcnt; pipeline cumsum loads
# speedup vs baseline: 1.0236x; 1.0236x over previous
; #define LAS __attribute__((address_space(3)))
; __global__ void __launch_bounds__(512, 2) fox_fwd(Args args) {
;     ...
;     if (args.ph_hi - args.ph_lo > 1) grid.sync();
;     if (IN(0)) { PTRS TIDS
;         LAS float* scr = (LAS float*)(lds3 + wave * 16384);
;         const int gw = bx * 8 + wave, NGW = G * 8;
;         constexpr int I_GU = (DM / 64) * (DFF / 32), I_DN = (DFF / 64) * (DM / 32), I_INA = (DM / 64) * (3 * FOXW / 32), I_INP = (DM / 64) * (POOLW / 32), I_O = (DM / 64) * (DM / 32), I_PL = 4 * (256 / 64) * (256 / 32);
;         constexpr int NITEMS = 4 * I_GU + 2 * I_DN + I_INA + I_INP + I_O + I_PL;
;         for (int it = gw; it < NITEMS; it += NGW) {
;             int r = it;
;             if (r < 4 * I_GU) {
;                 const int which = r / I_GU; r -= which * I_GU; const int nblk = DFF / 32, kb = r / nblk, nb = r % nblk, n0 = 32 * nb;
;                 const float* W = A_->in[which == 0 ? 7 : which == 1 ? 8 : which == 2 ? 17 : 18];
;                 bf16_t* WT = which < 2 ? Wgu1 : Wgu2; const int drow = (n0 >> 7) * 256 + (which & 1) * 128 + (n0 & 127);
;                 transpose_item(W + n0, DFF, WT, DM, drow, 64 * kb, scr, lane, which < 2 ? nullptr : A_->in[16]); continue; }
.LBB0_7:
	s_or_b64 exec, exec, s[8:9]
.LBB0_19:
	s_cmp_lt_i32 s44, 1
	s_cselect_b64 s[0:1], -1, 0
	s_cmp_gt_i32 s45, 0
	s_cselect_b64 s[4:5], -1, 0
	v_writelane_b32 v250, s54, 3
	s_and_b64 s[6:7], s[0:1], s[4:5]
	s_andn2_b64 vcc, exec, s[6:7]
	v_writelane_b32 v250, s55, 4
	v_writelane_b32 v250, s44, 5
	s_nop 1
	v_writelane_b32 v250, s45, 6
	s_cbranch_vccnz .LBB0_133
	s_mov_b64 s[22:23], s[54:55]
	s_load_dwordx2 s[20:21], s[22:23], 0xb0
	s_load_dwordx4 s[8:11], s[22:23], 0x0
	v_mov_b32_e32 v33, v182
	s_waitcnt lgkmcnt(0)
	s_add_u32 s24, s20, 0x4400000
	v_readfirstlane_b32 s0, v33
	s_addc_u32 s25, s21, 0
	s_ashr_i32 s3, s0, 6
	s_lshl_b32 s0, s2, 3
	s_add_i32 s16, s3, s0
	s_lshl_b32 s18, s48, 3
	s_cmp_gt_i32 s16, 0x9c7f
	v_and_b32_e32 v32, 63, v33
	s_cbranch_scc1 .LBB0_96
	v_and_b32_e32 v1, 7, v33
	s_lshl_b32 s0, s3, 14
	v_mov_b32_e32 v35, 0
	v_lshlrev_b32_e32 v34, 4, v1
	s_add_i32 s4, s0, 0
	v_lshrrev_b32_e32 v37, 3, v32
	v_lshl_add_u64 v[2:3], s[20:21], 0, v[34:35]
	s_mov_b64 s[0:1], 0x28800000
	v_lshlrev_b32_e32 v0, 2, v1
	v_add_u32_e32 v4, s4, v34
	v_mul_u32_u24_e32 v5, 0x84, v37
	v_lshlrev_b32_e32 v36, 3, v1
	v_mul_u32_u24_e32 v1, 0x420, v1
	v_lshl_add_u64 v[38:39], v[2:3], 0, s[0:1]
	v_lshlrev_b32_e32 v6, 2, v37
	s_mov_b64 s[0:1], 0x5500000
	v_add3_u32 v51, s4, v1, v6
	v_lshl_add_u64 v[40:41], v[2:3], 0, s[0:1]
	s_lshl_b32 s0, s2, 8
	s_lshl_b32 s1, s3, 5
	s_lshl_b32 s4, s2, 4
	s_lshl_b32 s3, s3, 1
	v_add_u32_e32 v52, v4, v5
	s_mov_b32 s27, 0
	v_or_b32_e32 v48, 8, v37
	v_or_b32_e32 v49, 16, v37
	v_or_b32_e32 v50, 24, v37
	v_lshl_add_u64 v[42:43], s[24:25], 0, v[34:35]
	s_add_i32 s0, s0, s1
	s_lshl_b32 s1, s48, 8
	s_add_i32 s3, s4, s3
	s_lshl_b32 s17, s48, 4
	s_mov_b64 s[28:29], 0x800000
	v_add_u32_e32 v53, 0x420, v52
	v_add_u32_e32 v54, 0x428, v52
	v_add_u32_e32 v55, 0x840, v52
	v_add_u32_e32 v56, 0x848, v52
	v_add_u32_e32 v57, 0xc60, v52
	v_add_u32_e32 v58, 0xc68, v52
	v_add_u32_e32 v59, 0x1080, v52
	v_add_u32_e32 v60, 0x1088, v52
	v_add_u32_e32 v61, 0x14a0, v52
	v_add_u32_e32 v62, 0x14a8, v52
	v_add_u32_e32 v63, 0x18c0, v52
	v_add_u32_e32 v64, 0x18c8, v52
	v_add_u32_e32 v65, 0x1ce0, v52
	v_add_u32_e32 v66, 0x1ce8, v52
	s_mov_b32 s19, 0x10000
	s_mov_b32 s33, 0x20000
	s_mov_b32 s38, 0x30000
	s_mov_b32 s39, 0x40000
	s_mov_b32 s40, 0x50000
	s_mov_b32 s41, 0x60000
	s_mov_b32 s42, 0x70000
	s_mov_b64 s[30:31], 0x3020
	s_movk_i32 s43, 0x4020
	s_movk_i32 s44, 0x48
	s_mov_b32 s45, 0x2e00000
	s_movk_i32 s46, 0x5800
	s_mov_b32 s47, 0x200000
	v_lshlrev_b32_e32 v44, 2, v0
	s_mov_b32 s50, s16
	s_branch .LBB0_24

;         nfull = (nwg / G) * G; R = nwg - nfull; SK = 1;
;         if (R > 0 && scratch_) { while (SK < 4 && R * SK * 2 <= G && (ntk / (SK * 2)) % 2 == 0 && ntk / (SK * 2) >= 4) SK *= 2; } }
;     __host__ __device__ __forceinline__ bool next(int i, Unit& u) const {
;         const int rf = nfull / G;
;         if (i < rf) { map(i * G + c, u); u.k0 = 0; u.nk = ntk; u.slot = -1; return true; }
;         if (i > rf) return false;
;         if (SK == 1) { const int L = nfull + c; if (L >= nwg) return false; map(L, u); u.k0 = 0; u.nk = ntk; u.slot = -1; return true; }
; __global__ void __launch_bounds__(512, 2) fox_fwd(Args args) {
;     ...
;     if (IN(3)) { PTRS TIDS pg8::Gemm g{ABUF, Win, MTOT, INWP, DM, DM, 0}; pg8::StaticOrder S; S.init(MTOT, INWP, DM, G, bx, 0, nullptr, nullptr);
;         pg8::EpiIn E{rowss1, out, Qb, Kb, Vb, Pb, A_->in[12], (float*)(ws + WS_NQ2), (float*)(ws + WS_NK2)}; pg8::gemm_phase(lds3, g, S, E); }
.LBB0_427:
	s_cmp_lt_i32 s44, 4
	s_cselect_b64 s[0:1], -1, 0
	s_waitcnt lgkmcnt(0)
	s_and_b64 s[14:15], s[0:1], s[4:5]
	s_andn2_b64 vcc, exec, s[14:15]
	s_cbranch_vccnz .LBB0_768
	s_abs_i32 s0, s48
	v_cvt_f32_u32_e32 v0, s0
	s_sub_i32 s3, 0, s0
	s_ashr_i32 s1, s48, 31
	s_mov_b64 s[4:5], s[54:55]
	v_rcp_iflag_f32_e32 v0, v0
	v_mov_b32_e32 v1, v182
	v_mov_b32_e32 v8, v182
	v_mul_f32_e32 v0, 0x4f7ffffe, v0
	v_cvt_u32_f32_e32 v0, v0
	s_nop 0
	v_readfirstlane_b32 s6, v0
	s_mul_i32 s3, s3, s6
	s_mul_hi_u32 s3, s6, s3
	s_add_i32 s6, s6, s3
	s_mul_hi_u32 s3, s6, 0x8a2
	s_mul_i32 s6, s3, s0
	s_sub_i32 s6, 0x8a2, s6
	s_add_i32 s7, s3, 1
	s_sub_i32 s8, s6, s0
	s_cmp_ge_u32 s6, s0
	s_cselect_b32 s3, s7, s3
	s_cselect_b32 s6, s8, s6
	s_add_i32 s7, s3, 1
	s_cmp_ge_u32 s6, s0
	s_cselect_b32 s0, s7, s3
	s_xor_b32 s0, s0, s1
	s_sub_i32 s33, s0, s1
	s_mul_i32 s0, s33, s48
	s_cmp_lt_i32 s33, 1
	v_readfirstlane_b32 s1, v8
	s_cbranch_scc0 .LBB0_433
	s_mov_b64 s[6:7], 0
	s_cmp_lt_i32 s33, 0
	s_mov_b64 s[8:9], 0
	s_cbranch_scc1 .LBB0_435
	s_add_i32 s3, s0, s2
	s_cmpk_gt_i32 s3, 0x8a1
	s_cbranch_scc1 .LBB0_434
	s_ashr_i32 s8, s3, 31
	s_lshr_b32 s8, s8, 29
	s_add_i32 s10, s3, s8
	s_and_b32 s8, s10, -8
	s_sub_i32 s3, s3, s8
	s_cmp_gt_i32 s3, 1
	s_cbranch_scc0 .LBB0_814
	s_mul_i32 s8, s3, 0x114
	s_or_b32 s11, s8, 2
	s_mov_b64 s[8:9], 0
	s_branch .LBB0_815

;     __device__ __forceinline__ void row(const f32x4 (&v)[2][2], const Unit& u, int row, int wc, int fq, float rq) const {
;         const int sec = u.pn >> 2, cbase = (u.pn & 3) * BM + wc * 32 + 8 * fq; const bool samp = u.pm >= MP / BM;
;         const float rs = 1.0f / sqrtf(rq * (1.0f / DM) + EPS);
;         size_t hm; int hs;
;         if (!samp) { const int b = row >> 13, t = row & (SEQ - 1); hm = ((size_t)b * NH * SEQ + t) * HD; hs = SEQ * HD; }
;         else { const int ms = row - MP, b = ms >> 5, t = ms & 31; hm = (size_t)MP * FOXW + ((size_t)b * NH * ST + t) * HD; hs = ST * HD; }
; #pragma unroll
;         for (int bj = 0; bj < 2; ++bj) { const int col = cbase + bj * HALF; const f32x4 v0 = v[bj][0] * rs, v1 = v[bj][1] * rs;
;             const int h = col >> 7, d = col & 127;
;             if (sec < 2 && !samp) { float ss = (v0[0] * v0[0] + v0[1] * v0[1]) + (v0[2] * v0[2] + v0[3] * v0[3]) + (v1[0] * v1[0] + v1[1] * v1[1]) + (v1[2] * v1[2] + v1[3] * v1[3]);
;                 ss += __shfl_xor(ss, 16); ss += __shfl_xor(ss, 32); if (fq == 0) atomicAdd((sec == 0 ? NQ2 : NK2) + (size_t)row * NH + h, ss); }
.LBB0_464:
	s_waitcnt vmcnt(8)
	v_fmamk_f32 v128, v128, 0x3a000000, v185
	v_mul_f32_e32 v129, 0x4f800000, v128
	v_cmp_gt_f32_e32 vcc, s47, v128
	s_lshl_b32 s10, s12, 8
	s_ashr_i32 s17, s12, 2
	v_cndmask_b32_e32 v128, v128, v129, vcc
	v_sqrt_f32_e32 v129, v128
	s_and_b32 s65, s10, 0x300
	s_cmp_gt_i32 s17, 1
	s_cselect_b64 s[10:11], -1, 0
	v_add_u32_e32 v130, -1, v129
	v_fma_f32 v131, -v130, v129, v128
	s_or_b64 s[14:15], s[8:9], s[10:11]
	v_cmp_ge_f32_e64 s[10:11], 0, v131
	v_add_u32_e32 v131, 1, v129
	s_cmp_lt_u32 s12, 4
	v_cndmask_b32_e64 v130, v129, v130, s[10:11]
	v_fma_f32 v129, -v131, v129, v128
	v_cmp_lt_f32_e64 s[10:11], 0, v129
	s_cselect_b64 s[72:73], -1, 0
	s_cmp_gt_u32 s12, 3
	v_cndmask_b32_e64 v129, v130, v131, s[10:11]
	v_mul_f32_e32 v130, 0x37800000, v129
	v_cndmask_b32_e32 v129, v129, v130, vcc
	v_cmp_class_f32_e32 vcc, v128, v186
	v_ashrrev_i32_e32 v161, 31, v160
	v_lshlrev_b64 v[164:165], 5, v[160:161]
	v_cndmask_b32_e32 v128, v129, v128, vcc
	v_div_scale_f32 v129, s[10:11], v128, v128, 1.0
	v_rcp_f32_e32 v130, v129
	s_cselect_b64 s[10:11], -1, 0
	s_lshr_b32 s63, s65, 7
	v_fma_f32 v131, -v129, v130, 1.0
	v_fmac_f32_e32 v130, v131, v130
	v_div_scale_f32 v131, vcc, 1.0, v128, 1.0
	v_mul_f32_e32 v132, v131, v130
	v_fma_f32 v133, -v129, v132, v131
	v_fmac_f32_e32 v132, v133, v130
	v_fma_f32 v129, -v129, v132, v131
	v_div_fmas_f32 v129, v129, v130, v132
	v_div_fixup_f32 v170, v129, v128, 1.0
	v_pk_mul_f32 v[122:123], v[170:171], v[122:123] op_sel_hi:[0,1]
	v_pk_mul_f32 v[120:121], v[170:171], v[120:121] op_sel_hi:[0,1]
	v_pk_mul_f32 v[126:127], v[170:171], v[126:127] op_sel_hi:[0,1]
	v_pk_mul_f32 v[124:125], v[170:171], v[124:125] op_sel_hi:[0,1]
	s_and_b64 vcc, exec, s[14:15]
	s_cbranch_vccnz .LBB0_468
	v_mul_f32_e32 v128, v121, v121
	v_mul_f32_e32 v129, v123, v123
	v_fmac_f32_e32 v128, v120, v120
	v_fmac_f32_e32 v129, v122, v122
	v_add_f32_e32 v128, v128, v129
	v_mul_f32_e32 v129, v125, v125
	v_fmac_f32_e32 v129, v124, v124
	v_add_f32_e32 v128, v129, v128
	v_mul_f32_e32 v129, v127, v127
	v_fmac_f32_e32 v129, v126, v126
	v_and_b32_e32 v130, 64, v187
	v_add_f32_e32 v128, v129, v128
	v_xor_b32_e32 v129, 16, v187
	v_add_u32_e32 v130, 64, v130
	v_cmp_lt_i32_e32 vcc, v129, v130
	s_nop 1
	v_cndmask_b32_e32 v129, v187, v129, vcc
	v_lshlrev_b32_e32 v129, 2, v129
	ds_bpermute_b32 v129, v129, v128
	s_waitcnt lgkmcnt(0)
	v_add_f32_e32 v128, v128, v129
	v_xor_b32_e32 v129, 32, v187
	v_cmp_lt_i32_e32 vcc, v129, v130
	s_nop 1
	v_cndmask_b32_e32 v129, v187, v129, vcc
	v_lshlrev_b32_e32 v129, 2, v129
	ds_bpermute_b32 v129, v129, v128
	s_and_saveexec_b64 s[12:13], s[4:5]
	s_cbranch_execz .LBB0_467
	s_and_b64 s[74:75], s[72:73], exec
	s_cselect_b32 s75, s95, s97
	s_cselect_b32 s74, s94, s96
	v_lshl_add_u64 v[130:131], s[74:75], 0, v[164:165]
	s_lshl_b32 s30, s63, 2
	v_lshl_add_u64 v[130:131], v[130:131], 0, s[30:31]
	s_waitcnt lgkmcnt(0)
	v_add_f32_e32 v128, v128, v129
	global_atomic_add_f32 v[130:131], v128, off

; __device__ __forceinline__ float ld_agent(const float* p) { return __hip_atomic_load(p, __ATOMIC_RELAXED, __HIP_MEMORY_SCOPE_AGENT); }
; __global__ void __launch_bounds__(512, 2) fox_fwd(Args args) {
;     ...
;         if (bx >= G - 32 && wave == 0) {
;             const int bh = bx - (G - 32), b = bh >> 3, h = bh & 7; const float* lf = out + O_LFP + (size_t)b * SEQ * NH + h; float* c = Cp + (size_t)bh * SEQ; float carry = 0.f;
;             const float* nq = (const float*)(ws + WS_NQ2) + (size_t)b * SEQ * NH + h; const float* nk = (const float*)(ws + WS_NK2) + (size_t)b * SEQ * NH + h;
;             float* QN = (float*)(ws + WS_QN) + bh * 32; float* KN = (float*)(ws + WS_KN) + bh; float qmax = 0.f, kmax = 0.f;
;             for (int ch = 0; ch < SEQ / 64; ++ch) { float v = lf[(size_t)(ch * 64 + lane) * NH];
;                 qmax = fmaxf(qmax, ld_agent(nq + (size_t)(ch * 64 + lane) * NH)); kmax = fmaxf(kmax, ld_agent(nk + (size_t)(ch * 64 + lane) * NH));
.LBB0_867:
	s_sub_i32 s1, s48, 32
	s_cmp_ge_i32 s2, s1
	s_cselect_b64 s[4:5], -1, 0
	s_cmp_lt_u32 s0, 64
	s_cselect_b64 s[6:7], -1, 0
	s_and_b64 s[4:5], s[4:5], s[6:7]
	s_andn2_b64 vcc, exec, s[4:5]
	s_waitcnt vmcnt(0) lgkmcnt(0)
	s_barrier
	s_cbranch_vccnz .LBB0_877
	v_mbcnt_lo_u32_b32 v0, -1, 0
	v_mbcnt_hi_u32_b32 v0, -1, v0
	v_and_b32_e32 v1, 64, v0
	v_add_u32_e32 v3, -1, v0
	v_cmp_lt_i32_e32 vcc, v3, v1
	v_bfrev_b32_e32 v2, 0.5
	v_lshl_or_b32 v8, v0, 2, v2
	v_cndmask_b32_e32 v3, v3, v0, vcc
	v_lshlrev_b32_e32 v9, 2, v3
	v_add_u32_e32 v3, -2, v0
	v_cmp_lt_i32_e32 vcc, v3, v1
	v_add_u32_e32 v2, 64, v1
	s_sub_i32 s24, s2, s1
	v_cndmask_b32_e32 v3, v3, v0, vcc
	v_lshlrev_b32_e32 v10, 2, v3
	v_add_u32_e32 v3, -4, v0
	v_cmp_lt_i32_e32 vcc, v3, v1
	s_mov_b32 s27, 0
	s_mov_b32 s25, s27
	v_cndmask_b32_e32 v3, v3, v0, vcc
	v_lshlrev_b32_e32 v11, 2, v3
	v_add_u32_e32 v3, -8, v0
	v_cmp_lt_i32_e32 vcc, v3, v1
	s_lshl_b32 s4, s24, 5
	s_mov_b32 s5, s27
	v_cndmask_b32_e32 v3, v3, v0, vcc
	v_lshlrev_b32_e32 v12, 2, v3
	v_add_u32_e32 v3, -16, v0
	v_cmp_lt_i32_e32 vcc, v3, v1
	s_lshr_b32 s26, s24, 3
	s_and_b32 s3, s24, 7
	v_cndmask_b32_e32 v3, v3, v0, vcc
	v_lshlrev_b32_e32 v13, 2, v3
	v_subrev_u32_e32 v3, 32, v0
	v_cmp_lt_i32_e32 vcc, v3, v1
	s_lshl_b64 s[0:1], s[24:25], 15
	s_lshl_b64 s[4:5], s[4:5], 2
	v_cndmask_b32_e32 v1, v3, v0, vcc
	v_lshlrev_b32_e32 v14, 2, v1
	v_xor_b32_e32 v1, 1, v0
	v_cmp_lt_i32_e32 vcc, v1, v2
	s_add_u32 s4, s18, s4
	s_addc_u32 s5, s19, s5
	v_cndmask_b32_e32 v1, v0, v1, vcc
	v_lshlrev_b32_e32 v15, 2, v1
	v_xor_b32_e32 v1, 2, v0
	v_cmp_lt_i32_e32 vcc, v1, v2
	s_add_u32 s28, s4, 0x6000
	s_addc_u32 s29, s5, 0
	v_cndmask_b32_e32 v1, v0, v1, vcc
	v_lshlrev_b32_e32 v16, 2, v1
	v_xor_b32_e32 v1, 4, v0
	v_cmp_lt_i32_e32 vcc, v1, v2
	v_and_b32_e32 v4, 63, v136
	s_add_u32 s0, s18, s0
	v_cndmask_b32_e32 v1, v0, v1, vcc
	v_lshlrev_b32_e32 v17, 2, v1
	v_xor_b32_e32 v1, 8, v0
	v_cmp_lt_i32_e32 vcc, v1, v2
	s_addc_u32 s1, s19, s1
	v_cmp_eq_u32_e64 s[4:5], 0, v4
	v_cndmask_b32_e32 v1, v0, v1, vcc
	v_lshlrev_b32_e32 v18, 2, v1
	v_xor_b32_e32 v1, 16, v0
	v_cmp_lt_i32_e32 vcc, v1, v2
	v_cmp_gt_u32_e64 s[6:7], 2, v4
	v_cmp_gt_u32_e64 s[8:9], 4, v4
	v_cndmask_b32_e32 v1, v0, v1, vcc
	v_lshlrev_b32_e32 v19, 2, v1
	v_xor_b32_e32 v1, 32, v0
	v_cmp_lt_i32_e32 vcc, v1, v2
	v_cmp_gt_u32_e64 s[10:11], 8, v4
	v_cmp_gt_u32_e64 s[12:13], 16, v4
	v_cndmask_b32_e32 v0, v0, v1, vcc
	v_lshlrev_b32_e32 v20, 2, v0
	v_lshlrev_b32_e32 v0, 2, v4
	v_mov_b32_e32 v1, 0
	v_lshl_add_u64 v[2:3], s[0:1], 0, v[0:1]
	s_mov_b64 s[0:1], 0x34b00000
	v_lshl_add_u64 v[2:3], v[2:3], 0, s[0:1]
	s_lshl_b64 s[0:1], s[26:27], 18
	v_lshl_or_b32 v0, v4, 5, s0
	v_lshl_or_b32 v6, s3, 2, v0
	v_mov_b32_e32 v7, s1
	v_cmp_gt_u32_e64 s[14:15], 32, v4
	v_lshl_add_u64 v[4:5], s[16:17], 0, v[6:7]
	s_mov_b64 s[0:1], 0x20400000
	v_lshl_add_u64 v[4:5], v[4:5], 0, s[0:1]
	v_lshl_add_u64 v[6:7], s[18:19], 0, v[6:7]
	s_mov_b64 s[30:31], 0
	s_mov_b64 s[34:35], 0x100
	v_mov_b32_e32 v21, v1
	v_mov_b32_e32 v0, v1
	global_load_dword v30, v[4:5], off
	v_add_co_u32_e32 v24, vcc, 0x34c00000, v6
	s_nop 1
	v_addc_co_u32_e32 v25, vcc, 0, v7, vcc
	global_load_dword v31, v[24:25], off sc1
	v_add_co_u32_e32 v22, vcc, 0x34e00000, v6
	s_nop 1
	v_addc_co_u32_e32 v23, vcc, 0, v7, vcc
	global_load_dword v32, v[22:23], off sc1
	s_waitcnt vmcnt(0)
	s_branch .LBB0_871

; __device__ __forceinline__ float ld_agent(const float* p) { return __hip_atomic_load(p, __ATOMIC_RELAXED, __HIP_MEMORY_SCOPE_AGENT); }
; __global__ void __launch_bounds__(512, 2) fox_fwd(Args args) {
;     ...
;             for (int ch = 0; ch < SEQ / 64; ++ch) { float v = lf[(size_t)(ch * 64 + lane) * NH];
;                 qmax = fmaxf(qmax, ld_agent(nq + (size_t)(ch * 64 + lane) * NH)); kmax = fmaxf(kmax, ld_agent(nk + (size_t)(ch * 64 + lane) * NH));
; #pragma unroll
;                 for (int o = 1; o < 64; o <<= 1) { const float t = __shfl_up(v, o); if (lane >= o) v += t; }
;                 v += carry; carry = __shfl(v, 63); c[ch * 64 + lane] = v;
;                 if ((ch & 3) == 3) {
; #pragma unroll
;                     for (int o = 1; o < 64; o <<= 1) qmax = fmaxf(qmax, __shfl_xor(qmax, o));
;                     if (lane == 0) QN[ch >> 2] = qmax; qmax = 0.f; } }
; #pragma unroll
;             for (int o = 1; o < 64; o <<= 1) kmax = fmaxf(kmax, __shfl_xor(kmax, o));
;             if (lane == 0) *KN = kmax;
.LBB0_870:
	s_add_i32 s27, s27, 1
	s_add_u32 s30, s30, 0x800
	v_max_f32_e32 v34, v34, v34
	v_max_f32_e32 v0, v0, v0
	s_addc_u32 s31, s31, 0
	v_max_f32_e32 v0, v0, v34
	s_cmp_eq_u32 s30, 0x40000
	v_lshl_add_u64 v[2:3], v[2:3], 0, s[34:35]
	s_cbranch_scc1 .LBB0_874
.LBB0_871:
	s_waitcnt vmcnt(1)
	v_mov_b32_e32 v26, v30
	v_mov_b32_e32 v33, v31
	v_mov_b32_e32 v34, v32
	s_add_u32 s36, s30, 0x800
	s_addc_u32 s37, s31, 0
	s_waitcnt lgkmcnt(0)
	v_lshl_add_u64 v[22:23], v[4:5], 0, s[36:37]
	global_load_dword v30, v[22:23], off
	v_lshl_add_u64 v[22:23], v[6:7], 0, s[36:37]
	v_add_co_u32_e32 v24, vcc, 0x34c00000, v22
	v_max_f32_e32 v21, v21, v21
	s_nop 0
	v_addc_co_u32_e32 v25, vcc, 0, v23, vcc
	global_load_dword v31, v[24:25], off sc1
	v_add_co_u32_e32 v22, vcc, 0x34e00000, v22
	s_and_b32 s0, s27, 3
	s_nop 0
	v_addc_co_u32_e32 v23, vcc, 0, v23, vcc
	global_load_dword v32, v[22:23], off sc1
	s_cmp_lg_u32 s0, 3
	ds_bpermute_b32 v23, v9, v26
	s_waitcnt lgkmcnt(0)
	v_add_f32_e32 v23, v26, v23
	v_cndmask_b32_e64 v23, v23, v26, s[4:5]
	ds_bpermute_b32 v25, v10, v23
	v_max_f32_e32 v33, v33, v33
	v_max_f32_e32 v21, v21, v33
	s_waitcnt lgkmcnt(0)
	v_add_f32_e32 v25, v23, v25
	v_cndmask_b32_e64 v23, v25, v23, s[6:7]
	ds_bpermute_b32 v25, v11, v23
	s_waitcnt lgkmcnt(0)
	v_add_f32_e32 v25, v23, v25
	v_cndmask_b32_e64 v23, v25, v23, s[8:9]
	ds_bpermute_b32 v25, v12, v23
	s_waitcnt lgkmcnt(0)
	v_add_f32_e32 v25, v23, v25
	v_cndmask_b32_e64 v23, v25, v23, s[10:11]
	ds_bpermute_b32 v25, v13, v23
	s_waitcnt lgkmcnt(0)
	v_add_f32_e32 v25, v23, v25
	v_cndmask_b32_e64 v23, v25, v23, s[12:13]
	ds_bpermute_b32 v25, v14, v23
	s_waitcnt lgkmcnt(0)
	v_add_f32_e32 v25, v23, v25
	v_cndmask_b32_e64 v23, v25, v23, s[14:15]
	v_add_f32_e32 v23, v1, v23
	ds_bpermute_b32 v1, v8, v23
	global_store_dword v[2:3], v23, off
	s_cbranch_scc1 .LBB0_870
	ds_bpermute_b32 v23, v15, v21
	v_max_f32_e32 v21, v21, v21
	s_waitcnt lgkmcnt(0)
	v_max_f32_e32 v23, v23, v23
	v_max_f32_e32 v21, v21, v23
	ds_bpermute_b32 v23, v16, v21
	s_waitcnt lgkmcnt(0)
	v_max_f32_e32 v23, v23, v23
	v_max_f32_e32 v21, v21, v23
	ds_bpermute_b32 v23, v17, v21
	s_waitcnt lgkmcnt(0)
	v_max_f32_e32 v23, v23, v23
	v_max_f32_e32 v21, v21, v23
	ds_bpermute_b32 v23, v18, v21
	s_waitcnt lgkmcnt(0)
	v_max_f32_e32 v23, v23, v23
	v_max_f32_e32 v21, v21, v23
	ds_bpermute_b32 v23, v19, v21
	s_waitcnt lgkmcnt(0)
	v_max_f32_e32 v23, v23, v23
	v_max_f32_e32 v21, v21, v23
	ds_bpermute_b32 v23, v20, v21
	s_and_saveexec_b64 s[36:37], s[4:5]
	s_cbranch_execz .LBB0_869
	s_waitcnt lgkmcnt(0)
	v_max_f32_e32 v23, v23, v23
	v_max_f32_e32 v21, v21, v21
	s_and_b32 s0, s27, -4
	v_max_f32_e32 v21, v21, v23
	v_mov_b32_e32 v23, s0
	global_store_dword v23, v21, s[28:29]
	s_branch .LBB0_869
.LBB0_874:
	s_waitcnt vmcnt(0) lgkmcnt(0)
	ds_bpermute_b32 v1, v15, v0
	v_max_f32_e32 v0, v0, v0
	s_waitcnt lgkmcnt(0)
	v_max_f32_e32 v1, v1, v1
	v_max_f32_e32 v0, v0, v1
	ds_bpermute_b32 v1, v16, v0
	s_waitcnt lgkmcnt(0)
	v_max_f32_e32 v1, v1, v1
	v_max_f32_e32 v0, v0, v1
	ds_bpermute_b32 v1, v17, v0
	s_waitcnt lgkmcnt(0)
	v_max_f32_e32 v1, v1, v1
	v_max_f32_e32 v0, v0, v1
	ds_bpermute_b32 v1, v18, v0
	s_waitcnt lgkmcnt(0)
	v_max_f32_e32 v1, v1, v1
	v_max_f32_e32 v0, v0, v1
	ds_bpermute_b32 v1, v19, v0
	s_waitcnt lgkmcnt(0)
	v_max_f32_e32 v1, v1, v1
	v_max_f32_e32 v0, v0, v1
	ds_bpermute_b32 v1, v20, v0
	s_and_saveexec_b64 s[6:7], s[4:5]
	s_cbranch_execz .LBB0_876
	s_lshl_b64 s[0:1], s[24:25], 2
	s_add_u32 s0, s18, s0
	s_waitcnt lgkmcnt(0)
	v_max_f32_e32 v1, v1, v1
	v_max_f32_e32 v0, v0, v0
	s_addc_u32 s1, s19, s1
	v_max_f32_e32 v0, v0, v1
	v_mov_b32_e32 v1, 0x8000
	global_store_dword v1, v0, s[0:1]

; __device__ __forceinline__ void block(const BlockRef& cur, const BlockRef& nxt, char* lds, Seam& S) {
;     ...
;     if (wid == 0) { const float lim = -(88.0f + 2.0f * cur.nrm) * INV_SCALE; const int t1 = lane + 64;
;         const bool d0 = lane < NTC && bias[64 * lane + 63] < lim, d1 = t1 < NTC && bias[64 * t1 + 63] < lim;
;         int cnt = __popcll(__ballot(d0)) + __popcll(__ballot(d1)); cnt &= ~1; if (cnt > NTC - 4) cnt = NTC - 4;
;         if (lane == 0) *jl = cnt; }
.LBB0_1125:
	s_or_b64 exec, exec, s[6:7]
	s_lshr_b32 s58, s43, 6
	v_and_b32_e32 v175, 63, v174
	s_cmp_lt_u32 s66, 64
	s_waitcnt lgkmcnt(0)
	s_barrier
	s_cbranch_scc0 .LBB0_1133
	v_fmaak_f32 v0, 2.0, v172, 0x42380000
	v_mul_f32_e32 v0, 0xc13504f3, v0
	v_cmp_gt_u32_e32 vcc, s58, v175
	s_mov_b64 s[6:7], 0
	s_mov_b64 s[8:9], 0
	s_and_saveexec_b64 s[44:45], vcc
	s_cbranch_execz .LBB0_1128
	v_lshl_add_u32 v1, v175, 8, s63
	ds_read_b32 v1, v1 offset:252
	s_waitcnt lgkmcnt(0)
	v_cmp_lt_f32_e32 vcc, v1, v0
	s_and_b64 s[8:9], vcc, exec

; __device__ __forceinline__ unsigned cvt_pk_bf16(float lo, float hi) { unsigned r; asm volatile("v_cvt_pk_bf16_f32 %0, %1, %2" : "=v"(r) : "v"(lo), "v"(hi)); return r; }
; __device__ __forceinline__ float ld_agent(const float* p) { return __hip_atomic_load(p, __ATOMIC_RELAXED, __HIP_MEMORY_SCOPE_AGENT); }
;     __device__ __forceinline__ void pre(const Unit& u, int wr, int fr, float (&r)[8]) const {
; #pragma unroll
;         for (int i = 0; i < 8; ++i) r[i] = rowss ? ld_agent(rowss + u.pm * BM + wr * 64 + fr + (i >> 2) * HALF + (i & 3) * 16) : 0.f; }
;     __device__ __forceinline__ void row(const f32x4 (&v)[2][2], const Unit& u, int row, int wc, int fq, float rq) const {
;         const int col0 = u.pn * 128 + wc * 32 + 8 * fq; const float rs = rowss ? 1.0f / sqrtf(rq * (1.0f / DM) + EPS) : 1.0f;
;         const f32x4 g0 = v[0][0] * rs, g1 = v[0][1] * rs, u0 = v[1][0] * rs, u1 = v[1][1] * rs;
;         const f32x2 a = silu_mul2((f32x2){g0[0], g0[1]}, (f32x2){u0[0], u0[1]}), b = silu_mul2((f32x2){g0[2], g0[3]}, (f32x2){u0[2], u0[3]});
;         const f32x2 c = silu_mul2((f32x2){g1[0], g1[1]}, (f32x2){u1[0], u1[1]}), d = silu_mul2((f32x2){g1[2], g1[3]}, (f32x2){u1[2], u1[3]});
;         u32x4 w; w.x = cvt_pk_bf16(a.x, a.y); w.y = cvt_pk_bf16(b.x, b.y); w.z = cvt_pk_bf16(c.x, c.y); w.w = cvt_pk_bf16(d.x, d.y);
;         *(u32x4*)(H + (size_t)row * DFF + col0) = w;
.LBB0_1628:
	s_waitcnt vmcnt(8)
	v_fmamk_f32 v157, v157, 0x3a000000, v148
	v_mul_f32_e32 v158, 0x4f800000, v157
	v_cmp_gt_f32_e32 vcc, s53, v157
	v_fmamk_f32 v156, v156, 0x3a000000, v148
	v_fmamk_f32 v155, v155, 0x3a000000, v148
	v_cndmask_b32_e32 v157, v157, v158, vcc
	v_sqrt_f32_e32 v158, v157
	v_fmamk_f32 v154, v154, 0x3a000000, v148
	v_fmamk_f32 v153, v153, 0x3a000000, v148
	v_fmamk_f32 v152, v152, 0x3a000000, v148
	v_add_u32_e32 v159, -1, v158
	v_fma_f32 v161, -v159, v158, v157
	v_add_u32_e32 v160, 1, v158
	v_cmp_ge_f32_e64 s[4:5], 0, v161
	v_fmamk_f32 v151, v151, 0x3a000000, v148
	v_fmamk_f32 v150, v150, 0x3a000000, v148
	v_cndmask_b32_e64 v159, v158, v159, s[4:5]
	v_fma_f32 v158, -v160, v158, v157
	v_cmp_lt_f32_e64 s[4:5], 0, v158
	s_nop 1
	v_cndmask_b32_e64 v158, v159, v160, s[4:5]
	v_mul_f32_e32 v160, 0x4f800000, v156
	v_cmp_gt_f32_e64 s[4:5], s53, v156
	v_mul_f32_e32 v159, 0x37800000, v158
	v_cndmask_b32_e32 v158, v158, v159, vcc
	v_cndmask_b32_e64 v156, v156, v160, s[4:5]
	v_sqrt_f32_e32 v160, v156
	v_cmp_class_f32_e32 vcc, v157, v149
	s_nop 1
	v_cndmask_b32_e32 v158, v158, v157, vcc
	v_add_u32_e32 v157, -1, v160
	v_fma_f32 v159, -v157, v160, v156
	v_cmp_ge_f32_e32 vcc, 0, v159
	v_add_u32_e32 v159, 1, v160
	s_nop 0
	v_cndmask_b32_e32 v157, v160, v157, vcc
	v_fma_f32 v160, -v159, v160, v156
	v_cmp_lt_f32_e32 vcc, 0, v160
	v_mul_f32_e32 v160, 0x4f800000, v155
	s_nop 0
	v_cndmask_b32_e32 v157, v157, v159, vcc
	v_cmp_gt_f32_e32 vcc, s53, v155
	v_mul_f32_e32 v159, 0x37800000, v157
	v_cndmask_b32_e64 v157, v157, v159, s[4:5]
	v_cndmask_b32_e32 v155, v155, v160, vcc
	v_sqrt_f32_e32 v160, v155
	v_cmp_class_f32_e64 s[4:5], v156, v149
	s_nop 1
	v_cndmask_b32_e64 v164, v157, v156, s[4:5]
	v_add_u32_e32 v156, -1, v160
	v_fma_f32 v157, -v156, v160, v155
	v_cmp_ge_f32_e64 s[4:5], 0, v157
	v_add_u32_e32 v157, 1, v160
	v_fma_f32 v159, -v157, v160, v155
	v_cndmask_b32_e64 v156, v160, v156, s[4:5]
	v_cmp_lt_f32_e64 s[4:5], 0, v159
	v_mul_f32_e32 v159, 0x4f800000, v154
	s_nop 0
	v_cndmask_b32_e64 v156, v156, v157, s[4:5]
	v_cmp_gt_f32_e64 s[4:5], s53, v154
	v_mul_f32_e32 v157, 0x37800000, v156
	v_cndmask_b32_e32 v156, v156, v157, vcc
	v_cndmask_b32_e64 v154, v154, v159, s[4:5]
	v_sqrt_f32_e32 v159, v154
	v_cmp_class_f32_e32 vcc, v155, v149
	s_nop 1
	v_cndmask_b32_e32 v155, v156, v155, vcc
	v_add_u32_e32 v156, -1, v159
	v_fma_f32 v157, -v156, v159, v154
	v_cmp_ge_f32_e32 vcc, 0, v157
	v_add_u32_e32 v157, 1, v159
	s_nop 0
	v_cndmask_b32_e32 v156, v159, v156, vcc
	v_fma_f32 v159, -v157, v159, v154
	v_cmp_lt_f32_e32 vcc, 0, v159
	v_mul_f32_e32 v159, 0x4f800000, v153
	s_nop 0
	v_cndmask_b32_e32 v156, v156, v157, vcc
	v_cmp_gt_f32_e32 vcc, s53, v153
	v_mul_f32_e32 v157, 0x37800000, v156
	v_cndmask_b32_e64 v156, v156, v157, s[4:5]
	v_cndmask_b32_e32 v153, v153, v159, vcc
	v_sqrt_f32_e32 v159, v153
	v_cmp_class_f32_e64 s[4:5], v154, v149
	s_nop 1
	v_cndmask_b32_e64 v165, v156, v154, s[4:5]
	v_add_u32_e32 v154, -1, v159
	v_fma_f32 v156, -v154, v159, v153
	v_cmp_ge_f32_e64 s[4:5], 0, v156
	v_add_u32_e32 v156, 1, v159
	v_fma_f32 v157, -v156, v159, v153
	v_cndmask_b32_e64 v154, v159, v154, s[4:5]
	v_cmp_lt_f32_e64 s[4:5], 0, v157
	v_mul_f32_e32 v157, 0x4f800000, v152
	s_nop 0
	v_cndmask_b32_e64 v154, v154, v156, s[4:5]
	v_cmp_gt_f32_e64 s[4:5], s53, v152
	v_mul_f32_e32 v156, 0x37800000, v154
	v_cndmask_b32_e32 v154, v154, v156, vcc
	v_cndmask_b32_e64 v152, v152, v157, s[4:5]
	v_sqrt_f32_e32 v157, v152
	v_cmp_class_f32_e32 vcc, v153, v149
	s_nop 1
	v_cndmask_b32_e32 v154, v154, v153, vcc
	v_add_u32_e32 v153, -1, v157
	v_fma_f32 v156, -v153, v157, v152
	v_cmp_ge_f32_e32 vcc, 0, v156
	v_add_u32_e32 v156, 1, v157
	s_nop 0
	v_cndmask_b32_e32 v153, v157, v153, vcc
	v_fma_f32 v157, -v156, v157, v152
	v_cmp_lt_f32_e32 vcc, 0, v157
	v_mul_f32_e32 v157, 0x4f800000, v151
	s_nop 0
	v_cndmask_b32_e32 v153, v153, v156, vcc
	v_cmp_gt_f32_e32 vcc, s53, v151
	v_mul_f32_e32 v156, 0x37800000, v153
	v_cndmask_b32_e64 v153, v153, v156, s[4:5]
	v_cndmask_b32_e32 v151, v151, v157, vcc
	v_sqrt_f32_e32 v157, v151
	v_cmp_class_f32_e64 s[4:5], v152, v149
	s_nop 1
	v_cndmask_b32_e64 v153, v153, v152, s[4:5]
	v_add_u32_e32 v152, -1, v157
	v_fma_f32 v156, -v152, v157, v151
	v_cmp_ge_f32_e64 s[4:5], 0, v156
	v_add_u32_e32 v156, 1, v157
	s_nop 0
	v_cndmask_b32_e64 v152, v157, v152, s[4:5]
	v_fma_f32 v157, -v156, v157, v151
	v_cmp_lt_f32_e64 s[4:5], 0, v157
	v_mul_f32_e32 v157, 0x4f800000, v150
	s_nop 0
	v_cndmask_b32_e64 v152, v152, v156, s[4:5]
	v_cmp_gt_f32_e64 s[4:5], s53, v150
	v_mul_f32_e32 v156, 0x37800000, v152
	v_cndmask_b32_e32 v152, v152, v156, vcc
	v_cndmask_b32_e64 v150, v150, v157, s[4:5]
	v_sqrt_f32_e32 v157, v150
	v_cmp_class_f32_e32 vcc, v151, v149
	s_nop 1
	v_cndmask_b32_e32 v152, v152, v151, vcc
	v_add_u32_e32 v151, -1, v157
	v_fma_f32 v156, -v151, v157, v150
	v_cmp_ge_f32_e32 vcc, 0, v156
	v_add_u32_e32 v156, 1, v157
	s_nop 0
	v_cndmask_b32_e32 v151, v157, v151, vcc
	v_fma_f32 v157, -v156, v157, v150
	v_cmp_lt_f32_e32 vcc, 0, v157
	s_nop 1
	v_cndmask_b32_e32 v151, v151, v156, vcc
	v_mul_f32_e32 v156, 0x37800000, v151
	v_cndmask_b32_e64 v151, v151, v156, s[4:5]
	v_div_scale_f32 v159, s[4:5], v158, v158, 1.0
	v_rcp_f32_e32 v160, v159
	v_cmp_class_f32_e32 vcc, v150, v149
	v_lshl_or_b32 v156, s30, 7, v144
	v_ashrrev_i32_e32 v157, 31, v156
	v_fma_f32 v161, -v159, v160, 1.0
	v_cndmask_b32_e32 v150, v151, v150, vcc
	v_fmac_f32_e32 v160, v161, v160
	v_div_scale_f32 v161, vcc, 1.0, v158, 1.0
	v_mul_f32_e32 v162, v161, v160
	v_fma_f32 v163, -v159, v162, v161
	v_fmac_f32_e32 v162, v163, v160
	v_fma_f32 v159, -v159, v162, v161
	v_div_fmas_f32 v159, v159, v160, v162
; __device__ __forceinline__ unsigned cvt_pk_bf16(float lo, float hi) { unsigned r; asm volatile("v_cvt_pk_bf16_f32 %0, %1, %2" : "=v"(r) : "v"(lo), "v"(hi)); return r; }
; __device__ __forceinline__ float ld_agent(const float* p) { return __hip_atomic_load(p, __ATOMIC_RELAXED, __HIP_MEMORY_SCOPE_AGENT); }
; __device__ __forceinline__ f32x2 silu_mul2(f32x2 g, f32x2 u) {
;     f32x2 x = g * (-1.4426950408889634f); x.x = fminf(x.x, 60.f); x.y = fminf(x.y, 60.f);
;     f32x2 e; e.x = __builtin_amdgcn_exp2f(x.x); e.y = __builtin_amdgcn_exp2f(x.y);
;     const f32x2 d = e + 1.0f; const float r = __builtin_amdgcn_rcpf(d.x * d.y);
;     const f32x2 sg = (f32x2){d.y, d.x} * r;
;     return (g * u) * sg;
; }
;     __device__ __forceinline__ void pre(const Unit& u, int wr, int fr, float (&r)[8]) const {
; #pragma unroll
;         for (int i = 0; i < 8; ++i) r[i] = rowss ? ld_agent(rowss + u.pm * BM + wr * 64 + fr + (i >> 2) * HALF + (i & 3) * 16) : 0.f; }
;     __device__ __forceinline__ void row(const f32x4 (&v)[2][2], const Unit& u, int row, int wc, int fq, float rq) const {
;         const int col0 = u.pn * 128 + wc * 32 + 8 * fq; const float rs = rowss ? 1.0f / sqrtf(rq * (1.0f / DM) + EPS) : 1.0f;
;         const f32x4 g0 = v[0][0] * rs, g1 = v[0][1] * rs, u0 = v[1][0] * rs, u1 = v[1][1] * rs;
;         const f32x2 a = silu_mul2((f32x2){g0[0], g0[1]}, (f32x2){u0[0], u0[1]}), b = silu_mul2((f32x2){g0[2], g0[3]}, (f32x2){u0[2], u0[3]});
;         const f32x2 c = silu_mul2((f32x2){g1[0], g1[1]}, (f32x2){u1[0], u1[1]}), d = silu_mul2((f32x2){g1[2], g1[3]}, (f32x2){u1[2], u1[3]});
;         u32x4 w; w.x = cvt_pk_bf16(a.x, a.y); w.y = cvt_pk_bf16(b.x, b.y); w.z = cvt_pk_bf16(c.x, c.y); w.w = cvt_pk_bf16(d.x, d.y);
;         *(u32x4*)(H + (size_t)row * DFF + col0) = w;
	v_div_fixup_f32 v158, v159, v158, 1.0
	v_pk_mul_f32 v[124:125], v[158:159], v[124:125] op_sel_hi:[0,1]
	v_pk_mul_f32 v[160:161], v[124:125], s[18:19] op_sel_hi:[1,0]
	v_pk_mul_f32 v[126:127], v[158:159], v[126:127] op_sel_hi:[0,1]
	v_min_f32_e32 v159, 0x42700000, v160
	v_min_f32_e32 v161, 0x42700000, v161
	v_exp_f32_e32 v160, v159
	v_exp_f32_e32 v161, v161
	v_pk_mul_f32 v[122:123], v[158:159], v[122:123] op_sel_hi:[0,1]
	v_pk_mul_f32 v[120:121], v[158:159], v[120:121] op_sel_hi:[0,1]
	v_pk_mul_f32 v[116:117], v[158:159], v[116:117] op_sel_hi:[0,1]
	v_pk_add_f32 v[160:161], v[160:161], 1.0 op_sel_hi:[1,0]
	v_pk_mul_f32 v[116:117], v[116:117], v[124:125]
	v_mul_f32_e32 v159, v160, v161
	v_pk_mul_f32 v[118:119], v[158:159], v[118:119] op_sel_hi:[0,1]
	v_pk_mul_f32 v[118:119], v[118:119], v[126:127]
	v_pk_mul_f32 v[124:125], v[126:127], s[18:19] op_sel_hi:[1,0]
	v_pk_mul_f32 v[126:127], v[120:121], s[18:19] op_sel_hi:[1,0]
	v_min_f32_e32 v124, 0x42700000, v124
	v_min_f32_e32 v125, 0x42700000, v125
	v_min_f32_e32 v126, 0x42700000, v126
	v_min_f32_e32 v127, 0x42700000, v127
	v_rcp_f32_e32 v162, v159
	v_exp_f32_e32 v124, v124
	v_exp_f32_e32 v125, v125
	v_exp_f32_e32 v126, v126
	v_exp_f32_e32 v127, v127
	v_pk_mul_f32 v[112:113], v[158:159], v[112:113] op_sel_hi:[0,1]
	v_pk_mul_f32 v[114:115], v[158:159], v[114:115] op_sel_hi:[0,1]
	v_pk_mul_f32 v[158:159], v[160:161], v[162:163] op_sel:[1,0] op_sel_hi:[0,0]
	v_pk_add_f32 v[124:125], v[124:125], 1.0 op_sel_hi:[1,0]
	v_pk_add_f32 v[126:127], v[126:127], 1.0 op_sel_hi:[1,0]
	v_pk_mul_f32 v[116:117], v[116:117], v[158:159]
	v_mul_f32_e32 v158, v124, v125
	v_mul_f32_e32 v159, v126, v127
	v_pk_mul_f32 v[162:163], v[122:123], s[18:19] op_sel_hi:[1,0]
	v_rcp_f32_e32 v158, v158
	v_rcp_f32_e32 v160, v159
	v_min_f32_e32 v159, 0x42700000, v162
	v_min_f32_e32 v161, 0x42700000, v163
	v_exp_f32_e32 v162, v159
	v_exp_f32_e32 v163, v161
	v_pk_mul_f32 v[124:125], v[124:125], v[158:159] op_sel:[1,0] op_sel_hi:[0,0]
	v_pk_mul_f32 v[118:119], v[118:119], v[124:125]
	v_pk_mul_f32 v[124:125], v[126:127], v[160:161] op_sel:[1,0] op_sel_hi:[0,0]
	v_pk_add_f32 v[126:127], v[162:163], 1.0 op_sel_hi:[1,0]
	v_pk_mul_f32 v[114:115], v[114:115], v[122:123]
	v_mul_f32_e32 v158, v126, v127
	v_rcp_f32_e32 v158, v158
	v_pk_mul_f32 v[112:113], v[112:113], v[120:121]
	v_div_scale_f32 v122, s[4:5], v164, v164, 1.0
	v_pk_mul_f32 v[112:113], v[112:113], v[124:125]
	v_pk_mul_f32 v[120:121], v[126:127], v[158:159] op_sel:[1,0] op_sel_hi:[0,0]
	v_rcp_f32_e32 v123, v122
	v_add_u32_e32 v151, s34, v142
	v_pk_mul_f32 v[114:115], v[114:115], v[120:121]
	v_cvt_pk_bf16_f32 v116, v116, v117
	v_cvt_pk_bf16_f32 v117, v118, v119
	v_cvt_pk_bf16_f32 v118, v112, v113
	v_mov_b64_e32 v[112:113], s[10:11]
	v_cvt_pk_bf16_f32 v119, v114, v115
	v_mad_i64_i32 v[120:121], s[4:5], v151, s54, v[112:113]
	v_lshlrev_b64 v[114:115], 1, v[156:157]
	v_lshl_add_u64 v[120:121], v[120:121], 0, v[114:115]
	global_store_dwordx4 v[120:121], v[116:119], off
	v_or_b32_e32 v124, 16, v151
	s_nop 0
	v_fma_f32 v116, -v122, v123, 1.0
	v_fmac_f32_e32 v123, v116, v123
	v_div_scale_f32 v116, vcc, 1.0, v164, 1.0
	v_mul_f32_e32 v117, v116, v123
	v_fma_f32 v118, -v122, v117, v116
	v_fmac_f32_e32 v117, v118, v123
	v_fma_f32 v116, -v122, v117, v116
	v_div_fmas_f32 v116, v116, v123, v117
	v_div_fixup_f32 v116, v116, v164, 1.0
	v_pk_mul_f32 v[108:109], v[116:117], v[108:109] op_sel_hi:[0,1]
	v_pk_mul_f32 v[118:119], v[108:109], s[18:19] op_sel_hi:[1,0]
	v_pk_mul_f32 v[110:111], v[116:117], v[110:111] op_sel_hi:[0,1]
	v_min_f32_e32 v117, 0x42700000, v118
	v_min_f32_e32 v119, 0x42700000, v119
	v_exp_f32_e32 v118, v117
	v_exp_f32_e32 v119, v119
	v_pk_mul_f32 v[106:107], v[116:117], v[106:107] op_sel_hi:[0,1]
	v_pk_mul_f32 v[104:105], v[116:117], v[104:105] op_sel_hi:[0,1]
	v_pk_mul_f32 v[100:101], v[116:117], v[100:101] op_sel_hi:[0,1]
	v_pk_add_f32 v[118:119], v[118:119], 1.0 op_sel_hi:[1,0]
	v_pk_mul_f32 v[100:101], v[100:101], v[108:109]
	v_mul_f32_e32 v117, v118, v119
	v_pk_mul_f32 v[102:103], v[116:117], v[102:103] op_sel_hi:[0,1]
	v_pk_mul_f32 v[102:103], v[102:103], v[110:111]
	v_pk_mul_f32 v[108:109], v[110:111], s[18:19] op_sel_hi:[1,0]
	v_pk_mul_f32 v[110:111], v[104:105], s[18:19] op_sel_hi:[1,0]
	v_min_f32_e32 v108, 0x42700000, v108
	v_min_f32_e32 v109, 0x42700000, v109
	v_min_f32_e32 v110, 0x42700000, v110
	v_min_f32_e32 v111, 0x42700000, v111
	v_rcp_f32_e32 v120, v117
	v_exp_f32_e32 v108, v108
	v_exp_f32_e32 v109, v109
	v_exp_f32_e32 v110, v110
	v_exp_f32_e32 v111, v111
	v_pk_mul_f32 v[96:97], v[116:117], v[96:97] op_sel_hi:[0,1]
	v_pk_mul_f32 v[98:99], v[116:117], v[98:99] op_sel_hi:[0,1]
	v_pk_mul_f32 v[116:117], v[118:119], v[120:121] op_sel:[1,0] op_sel_hi:[0,0]
	v_pk_add_f32 v[108:109], v[108:109], 1.0 op_sel_hi:[1,0]
	v_pk_add_f32 v[110:111], v[110:111], 1.0 op_sel_hi:[1,0]
	v_pk_mul_f32 v[100:101], v[100:101], v[116:117]
	v_mul_f32_e32 v116, v108, v109
	v_mul_f32_e32 v117, v110, v111
	v_pk_mul_f32 v[120:121], v[106:107], s[18:19] op_sel_hi:[1,0]
	v_rcp_f32_e32 v116, v116
	v_rcp_f32_e32 v118, v117
	v_min_f32_e32 v117, 0x42700000, v120
	v_min_f32_e32 v119, 0x42700000, v121
	v_exp_f32_e32 v120, v117
	v_exp_f32_e32 v121, v119
	v_pk_mul_f32 v[108:109], v[108:109], v[116:117] op_sel:[1,0] op_sel_hi:[0,0]
	v_pk_mul_f32 v[102:103], v[102:103], v[108:109]
	v_pk_mul_f32 v[108:109], v[110:111], v[118:119] op_sel:[1,0] op_sel_hi:[0,0]
	v_pk_add_f32 v[110:111], v[120:121], 1.0 op_sel_hi:[1,0]
	v_pk_mul_f32 v[96:97], v[96:97], v[104:105]
	v_mul_f32_e32 v116, v110, v111
	v_rcp_f32_e32 v116, v116
	v_pk_mul_f32 v[98:99], v[98:99], v[106:107]
	v_pk_mul_f32 v[104:105], v[96:97], v[108:109]
; __device__ __forceinline__ unsigned cvt_pk_bf16(float lo, float hi) { unsigned r; asm volatile("v_cvt_pk_bf16_f32 %0, %1, %2" : "=v"(r) : "v"(lo), "v"(hi)); return r; }
; __device__ __forceinline__ float ld_agent(const float* p) { return __hip_atomic_load(p, __ATOMIC_RELAXED, __HIP_MEMORY_SCOPE_AGENT); }
; __device__ __forceinline__ f32x2 silu_mul2(f32x2 g, f32x2 u) {
;     f32x2 x = g * (-1.4426950408889634f); x.x = fminf(x.x, 60.f); x.y = fminf(x.y, 60.f);
;     f32x2 e; e.x = __builtin_amdgcn_exp2f(x.x); e.y = __builtin_amdgcn_exp2f(x.y);
;     const f32x2 d = e + 1.0f; const float r = __builtin_amdgcn_rcpf(d.x * d.y);
;     const f32x2 sg = (f32x2){d.y, d.x} * r;
;     return (g * u) * sg;
; }
;     __device__ __forceinline__ void pre(const Unit& u, int wr, int fr, float (&r)[8]) const {
; #pragma unroll
;         for (int i = 0; i < 8; ++i) r[i] = rowss ? ld_agent(rowss + u.pm * BM + wr * 64 + fr + (i >> 2) * HALF + (i & 3) * 16) : 0.f; }
;     __device__ __forceinline__ void row(const f32x4 (&v)[2][2], const Unit& u, int row, int wc, int fq, float rq) const {
;         const int col0 = u.pn * 128 + wc * 32 + 8 * fq; const float rs = rowss ? 1.0f / sqrtf(rq * (1.0f / DM) + EPS) : 1.0f;
;         const f32x4 g0 = v[0][0] * rs, g1 = v[0][1] * rs, u0 = v[1][0] * rs, u1 = v[1][1] * rs;
;         const f32x2 a = silu_mul2((f32x2){g0[0], g0[1]}, (f32x2){u0[0], u0[1]}), b = silu_mul2((f32x2){g0[2], g0[3]}, (f32x2){u0[2], u0[3]});
;         const f32x2 c = silu_mul2((f32x2){g1[0], g1[1]}, (f32x2){u1[0], u1[1]}), d = silu_mul2((f32x2){g1[2], g1[3]}, (f32x2){u1[2], u1[3]});
;         u32x4 w; w.x = cvt_pk_bf16(a.x, a.y); w.y = cvt_pk_bf16(b.x, b.y); w.z = cvt_pk_bf16(c.x, c.y); w.w = cvt_pk_bf16(d.x, d.y);
;         *(u32x4*)(H + (size_t)row * DFF + col0) = w;
	v_pk_mul_f32 v[96:97], v[110:111], v[116:117] op_sel:[1,0] op_sel_hi:[0,0]
	v_pk_mul_f32 v[106:107], v[98:99], v[96:97]
	v_cvt_pk_bf16_f32 v96, v100, v101
	v_cvt_pk_bf16_f32 v97, v102, v103
	v_div_scale_f32 v102, s[4:5], v155, v155, 1.0
	v_rcp_f32_e32 v103, v102
	v_mad_i64_i32 v[100:101], s[4:5], v124, s54, v[112:113]
	v_lshl_add_u64 v[100:101], v[100:101], 0, v[114:115]
	v_cvt_pk_bf16_f32 v98, v104, v105
	v_cvt_pk_bf16_f32 v99, v106, v107
	global_store_dwordx4 v[100:101], v[96:99], off
	v_or_b32_e32 v104, 32, v151
	s_nop 0
	v_fma_f32 v96, -v102, v103, 1.0
	v_fmac_f32_e32 v103, v96, v103
	v_div_scale_f32 v96, vcc, 1.0, v155, 1.0
	v_mul_f32_e32 v97, v96, v103
	v_fma_f32 v98, -v102, v97, v96
	v_fmac_f32_e32 v97, v98, v103
	v_fma_f32 v96, -v102, v97, v96
	v_div_fmas_f32 v96, v96, v103, v97
	v_div_fixup_f32 v96, v96, v155, 1.0
	v_pk_mul_f32 v[92:93], v[96:97], v[92:93] op_sel_hi:[0,1]
	v_pk_mul_f32 v[98:99], v[92:93], s[18:19] op_sel_hi:[1,0]
	v_pk_mul_f32 v[94:95], v[96:97], v[94:95] op_sel_hi:[0,1]
	v_min_f32_e32 v97, 0x42700000, v98
	v_min_f32_e32 v99, 0x42700000, v99
	v_exp_f32_e32 v98, v97
	v_exp_f32_e32 v99, v99
	v_pk_mul_f32 v[90:91], v[96:97], v[90:91] op_sel_hi:[0,1]
	v_pk_mul_f32 v[88:89], v[96:97], v[88:89] op_sel_hi:[0,1]
	v_pk_mul_f32 v[84:85], v[96:97], v[84:85] op_sel_hi:[0,1]
	v_pk_add_f32 v[98:99], v[98:99], 1.0 op_sel_hi:[1,0]
	v_pk_mul_f32 v[84:85], v[84:85], v[92:93]
	v_mul_f32_e32 v97, v98, v99
	v_pk_mul_f32 v[86:87], v[96:97], v[86:87] op_sel_hi:[0,1]
	v_pk_mul_f32 v[86:87], v[86:87], v[94:95]
	v_pk_mul_f32 v[92:93], v[94:95], s[18:19] op_sel_hi:[1,0]
	v_pk_mul_f32 v[94:95], v[88:89], s[18:19] op_sel_hi:[1,0]
	v_min_f32_e32 v92, 0x42700000, v92
	v_min_f32_e32 v93, 0x42700000, v93
	v_min_f32_e32 v94, 0x42700000, v94
	v_min_f32_e32 v95, 0x42700000, v95
	v_rcp_f32_e32 v100, v97
	v_exp_f32_e32 v92, v92
	v_exp_f32_e32 v93, v93
	v_exp_f32_e32 v94, v94
	v_exp_f32_e32 v95, v95
	v_pk_mul_f32 v[80:81], v[96:97], v[80:81] op_sel_hi:[0,1]
	v_pk_mul_f32 v[82:83], v[96:97], v[82:83] op_sel_hi:[0,1]
	v_pk_mul_f32 v[96:97], v[98:99], v[100:101] op_sel:[1,0] op_sel_hi:[0,0]
	v_pk_add_f32 v[92:93], v[92:93], 1.0 op_sel_hi:[1,0]
	v_pk_add_f32 v[94:95], v[94:95], 1.0 op_sel_hi:[1,0]
	v_pk_mul_f32 v[84:85], v[84:85], v[96:97]
	v_mul_f32_e32 v96, v92, v93
	v_mul_f32_e32 v97, v94, v95
	v_pk_mul_f32 v[100:101], v[90:91], s[18:19] op_sel_hi:[1,0]
	v_rcp_f32_e32 v96, v96
	v_rcp_f32_e32 v98, v97
	v_min_f32_e32 v97, 0x42700000, v100
	v_min_f32_e32 v99, 0x42700000, v101
	v_exp_f32_e32 v100, v97
	v_exp_f32_e32 v101, v99
	v_pk_mul_f32 v[92:93], v[92:93], v[96:97] op_sel:[1,0] op_sel_hi:[0,0]
	v_pk_mul_f32 v[86:87], v[86:87], v[92:93]
	v_pk_mul_f32 v[92:93], v[94:95], v[98:99] op_sel:[1,0] op_sel_hi:[0,0]
	v_pk_add_f32 v[94:95], v[100:101], 1.0 op_sel_hi:[1,0]
	v_pk_mul_f32 v[80:81], v[80:81], v[88:89]
	v_mul_f32_e32 v96, v94, v95
	v_rcp_f32_e32 v96, v96
	v_pk_mul_f32 v[82:83], v[82:83], v[90:91]
	v_pk_mul_f32 v[88:89], v[80:81], v[92:93]
	v_pk_mul_f32 v[80:81], v[94:95], v[96:97] op_sel:[1,0] op_sel_hi:[0,0]
	v_pk_mul_f32 v[90:91], v[82:83], v[80:81]
	v_cvt_pk_bf16_f32 v80, v84, v85
	v_cvt_pk_bf16_f32 v81, v86, v87
	v_div_scale_f32 v86, s[4:5], v165, v165, 1.0
	v_rcp_f32_e32 v87, v86
	v_mad_i64_i32 v[84:85], s[4:5], v104, s54, v[112:113]
	v_lshl_add_u64 v[84:85], v[84:85], 0, v[114:115]
	v_cvt_pk_bf16_f32 v82, v88, v89
	v_cvt_pk_bf16_f32 v83, v90, v91
	global_store_dwordx4 v[84:85], v[80:83], off
	v_or_b32_e32 v88, 48, v151
	s_nop 0
	v_fma_f32 v80, -v86, v87, 1.0
	v_fmac_f32_e32 v87, v80, v87
	v_div_scale_f32 v80, vcc, 1.0, v165, 1.0
	v_mul_f32_e32 v81, v80, v87
	v_fma_f32 v82, -v86, v81, v80
	v_fmac_f32_e32 v81, v82, v87
	v_fma_f32 v80, -v86, v81, v80
	v_div_fmas_f32 v80, v80, v87, v81
	v_div_fixup_f32 v80, v80, v165, 1.0
	v_pk_mul_f32 v[76:77], v[80:81], v[76:77] op_sel_hi:[0,1]
	v_pk_mul_f32 v[82:83], v[76:77], s[18:19] op_sel_hi:[1,0]
	v_pk_mul_f32 v[78:79], v[80:81], v[78:79] op_sel_hi:[0,1]
	v_min_f32_e32 v81, 0x42700000, v82
	v_min_f32_e32 v83, 0x42700000, v83
	v_exp_f32_e32 v82, v81
	v_exp_f32_e32 v83, v83
	v_pk_mul_f32 v[74:75], v[80:81], v[74:75] op_sel_hi:[0,1]
	v_pk_mul_f32 v[72:73], v[80:81], v[72:73] op_sel_hi:[0,1]
	v_pk_mul_f32 v[68:69], v[80:81], v[68:69] op_sel_hi:[0,1]
	v_pk_add_f32 v[82:83], v[82:83], 1.0 op_sel_hi:[1,0]
	v_pk_mul_f32 v[68:69], v[68:69], v[76:77]
	v_mul_f32_e32 v81, v82, v83
	v_pk_mul_f32 v[70:71], v[80:81], v[70:71] op_sel_hi:[0,1]
	v_pk_mul_f32 v[70:71], v[70:71], v[78:79]
	v_pk_mul_f32 v[76:77], v[78:79], s[18:19] op_sel_hi:[1,0]
	v_pk_mul_f32 v[78:79], v[72:73], s[18:19] op_sel_hi:[1,0]
	v_min_f32_e32 v76, 0x42700000, v76
	v_min_f32_e32 v77, 0x42700000, v77
	v_min_f32_e32 v78, 0x42700000, v78
	v_min_f32_e32 v79, 0x42700000, v79
	v_rcp_f32_e32 v84, v81
	v_exp_f32_e32 v76, v76
	v_exp_f32_e32 v77, v77
	v_exp_f32_e32 v78, v78
	v_exp_f32_e32 v79, v79
	v_pk_mul_f32 v[64:65], v[80:81], v[64:65] op_sel_hi:[0,1]
	v_pk_mul_f32 v[66:67], v[80:81], v[66:67] op_sel_hi:[0,1]
	v_pk_mul_f32 v[80:81], v[82:83], v[84:85] op_sel:[1,0] op_sel_hi:[0,0]
	v_pk_add_f32 v[76:77], v[76:77], 1.0 op_sel_hi:[1,0]
	v_pk_add_f32 v[78:79], v[78:79], 1.0 op_sel_hi:[1,0]
	v_pk_mul_f32 v[68:69], v[68:69], v[80:81]
	v_mul_f32_e32 v80, v76, v77
	v_mul_f32_e32 v81, v78, v79
	v_pk_mul_f32 v[84:85], v[74:75], s[18:19] op_sel_hi:[1,0]
	v_rcp_f32_e32 v80, v80
	v_rcp_f32_e32 v82, v81
	v_min_f32_e32 v81, 0x42700000, v84
	v_min_f32_e32 v83, 0x42700000, v85
	v_exp_f32_e32 v84, v81
	v_exp_f32_e32 v85, v83
	v_pk_mul_f32 v[76:77], v[76:77], v[80:81] op_sel:[1,0] op_sel_hi:[0,0]
	v_pk_mul_f32 v[70:71], v[70:71], v[76:77]
; __device__ __forceinline__ unsigned cvt_pk_bf16(float lo, float hi) { unsigned r; asm volatile("v_cvt_pk_bf16_f32 %0, %1, %2" : "=v"(r) : "v"(lo), "v"(hi)); return r; }
; __device__ __forceinline__ float ld_agent(const float* p) { return __hip_atomic_load(p, __ATOMIC_RELAXED, __HIP_MEMORY_SCOPE_AGENT); }
; __device__ __forceinline__ f32x2 silu_mul2(f32x2 g, f32x2 u) {
;     f32x2 x = g * (-1.4426950408889634f); x.x = fminf(x.x, 60.f); x.y = fminf(x.y, 60.f);
;     f32x2 e; e.x = __builtin_amdgcn_exp2f(x.x); e.y = __builtin_amdgcn_exp2f(x.y);
;     const f32x2 d = e + 1.0f; const float r = __builtin_amdgcn_rcpf(d.x * d.y);
;     const f32x2 sg = (f32x2){d.y, d.x} * r;
;     return (g * u) * sg;
; }
;     __device__ __forceinline__ void pre(const Unit& u, int wr, int fr, float (&r)[8]) const {
; #pragma unroll
;         for (int i = 0; i < 8; ++i) r[i] = rowss ? ld_agent(rowss + u.pm * BM + wr * 64 + fr + (i >> 2) * HALF + (i & 3) * 16) : 0.f; }
;     __device__ __forceinline__ void row(const f32x4 (&v)[2][2], const Unit& u, int row, int wc, int fq, float rq) const {
;         const int col0 = u.pn * 128 + wc * 32 + 8 * fq; const float rs = rowss ? 1.0f / sqrtf(rq * (1.0f / DM) + EPS) : 1.0f;
;         const f32x4 g0 = v[0][0] * rs, g1 = v[0][1] * rs, u0 = v[1][0] * rs, u1 = v[1][1] * rs;
;         const f32x2 a = silu_mul2((f32x2){g0[0], g0[1]}, (f32x2){u0[0], u0[1]}), b = silu_mul2((f32x2){g0[2], g0[3]}, (f32x2){u0[2], u0[3]});
;         const f32x2 c = silu_mul2((f32x2){g1[0], g1[1]}, (f32x2){u1[0], u1[1]}), d = silu_mul2((f32x2){g1[2], g1[3]}, (f32x2){u1[2], u1[3]});
;         u32x4 w; w.x = cvt_pk_bf16(a.x, a.y); w.y = cvt_pk_bf16(b.x, b.y); w.z = cvt_pk_bf16(c.x, c.y); w.w = cvt_pk_bf16(d.x, d.y);
;         *(u32x4*)(H + (size_t)row * DFF + col0) = w;
	v_pk_mul_f32 v[76:77], v[78:79], v[82:83] op_sel:[1,0] op_sel_hi:[0,0]
	v_pk_add_f32 v[78:79], v[84:85], 1.0 op_sel_hi:[1,0]
	v_pk_mul_f32 v[64:65], v[64:65], v[72:73]
	v_mul_f32_e32 v80, v78, v79
	v_rcp_f32_e32 v80, v80
	v_pk_mul_f32 v[66:67], v[66:67], v[74:75]
	v_pk_mul_f32 v[72:73], v[64:65], v[76:77]
	v_pk_mul_f32 v[64:65], v[78:79], v[80:81] op_sel:[1,0] op_sel_hi:[0,0]
	v_pk_mul_f32 v[74:75], v[66:67], v[64:65]
	v_cvt_pk_bf16_f32 v64, v68, v69
	v_cvt_pk_bf16_f32 v65, v70, v71
	v_div_scale_f32 v70, s[4:5], v154, v154, 1.0
	v_rcp_f32_e32 v71, v70
	v_mad_i64_i32 v[68:69], s[4:5], v88, s54, v[112:113]
	v_lshl_add_u64 v[68:69], v[68:69], 0, v[114:115]
	v_cvt_pk_bf16_f32 v66, v72, v73
	v_cvt_pk_bf16_f32 v67, v74, v75
	global_store_dwordx4 v[68:69], v[64:67], off
	v_add_u32_e32 v72, 0x80, v151
	s_nop 0
	v_fma_f32 v64, -v70, v71, 1.0
	v_fmac_f32_e32 v71, v64, v71
	v_div_scale_f32 v64, vcc, 1.0, v154, 1.0
	v_mul_f32_e32 v65, v64, v71
	v_fma_f32 v66, -v70, v65, v64
	v_fmac_f32_e32 v65, v66, v71
	v_fma_f32 v64, -v70, v65, v64
	v_div_fmas_f32 v64, v64, v71, v65
	v_div_fixup_f32 v64, v64, v154, 1.0
	v_pk_mul_f32 v[60:61], v[64:65], v[60:61] op_sel_hi:[0,1]
	v_pk_mul_f32 v[66:67], v[60:61], s[18:19] op_sel_hi:[1,0]
	v_pk_mul_f32 v[62:63], v[64:65], v[62:63] op_sel_hi:[0,1]
	v_min_f32_e32 v65, 0x42700000, v66
	v_min_f32_e32 v67, 0x42700000, v67
	v_exp_f32_e32 v66, v65
	v_exp_f32_e32 v67, v67
	v_pk_mul_f32 v[58:59], v[64:65], v[58:59] op_sel_hi:[0,1]
	v_pk_mul_f32 v[56:57], v[64:65], v[56:57] op_sel_hi:[0,1]
	v_pk_mul_f32 v[52:53], v[64:65], v[52:53] op_sel_hi:[0,1]
	v_pk_add_f32 v[66:67], v[66:67], 1.0 op_sel_hi:[1,0]
	v_pk_mul_f32 v[52:53], v[52:53], v[60:61]
	v_mul_f32_e32 v65, v66, v67
	v_pk_mul_f32 v[54:55], v[64:65], v[54:55] op_sel_hi:[0,1]
	v_pk_mul_f32 v[54:55], v[54:55], v[62:63]
	v_pk_mul_f32 v[60:61], v[62:63], s[18:19] op_sel_hi:[1,0]
	v_pk_mul_f32 v[62:63], v[56:57], s[18:19] op_sel_hi:[1,0]
	v_min_f32_e32 v60, 0x42700000, v60
	v_min_f32_e32 v61, 0x42700000, v61
	v_min_f32_e32 v62, 0x42700000, v62
	v_min_f32_e32 v63, 0x42700000, v63
	v_rcp_f32_e32 v68, v65
	v_exp_f32_e32 v60, v60
	v_exp_f32_e32 v61, v61
	v_exp_f32_e32 v62, v62
	v_exp_f32_e32 v63, v63
	v_pk_mul_f32 v[48:49], v[64:65], v[48:49] op_sel_hi:[0,1]
	v_pk_mul_f32 v[50:51], v[64:65], v[50:51] op_sel_hi:[0,1]
	v_pk_mul_f32 v[64:65], v[66:67], v[68:69] op_sel:[1,0] op_sel_hi:[0,0]
	v_pk_add_f32 v[60:61], v[60:61], 1.0 op_sel_hi:[1,0]
	v_pk_add_f32 v[62:63], v[62:63], 1.0 op_sel_hi:[1,0]
	v_pk_mul_f32 v[52:53], v[52:53], v[64:65]
	v_mul_f32_e32 v64, v60, v61
	v_mul_f32_e32 v65, v62, v63
	v_pk_mul_f32 v[68:69], v[58:59], s[18:19] op_sel_hi:[1,0]
	v_rcp_f32_e32 v64, v64
	v_rcp_f32_e32 v66, v65
	v_min_f32_e32 v65, 0x42700000, v68
	v_min_f32_e32 v67, 0x42700000, v69
	v_exp_f32_e32 v68, v65
	v_exp_f32_e32 v69, v67
	v_pk_mul_f32 v[60:61], v[60:61], v[64:65] op_sel:[1,0] op_sel_hi:[0,0]
	v_pk_mul_f32 v[54:55], v[54:55], v[60:61]
	v_pk_mul_f32 v[60:61], v[62:63], v[66:67] op_sel:[1,0] op_sel_hi:[0,0]
	v_pk_add_f32 v[62:63], v[68:69], 1.0 op_sel_hi:[1,0]
	v_pk_mul_f32 v[48:49], v[48:49], v[56:57]
	v_mul_f32_e32 v64, v62, v63
	v_rcp_f32_e32 v64, v64
	v_pk_mul_f32 v[50:51], v[50:51], v[58:59]
	v_pk_mul_f32 v[56:57], v[48:49], v[60:61]
	v_pk_mul_f32 v[48:49], v[62:63], v[64:65] op_sel:[1,0] op_sel_hi:[0,0]
	v_pk_mul_f32 v[58:59], v[50:51], v[48:49]
	v_cvt_pk_bf16_f32 v48, v52, v53
	v_cvt_pk_bf16_f32 v49, v54, v55
	v_div_scale_f32 v54, s[4:5], v153, v153, 1.0
	v_rcp_f32_e32 v55, v54
	v_mad_i64_i32 v[52:53], s[4:5], v72, s54, v[112:113]
	v_lshl_add_u64 v[52:53], v[52:53], 0, v[114:115]
	v_cvt_pk_bf16_f32 v50, v56, v57
	v_cvt_pk_bf16_f32 v51, v58, v59
	global_store_dwordx4 v[52:53], v[48:51], off
	v_add_u32_e32 v56, 0x90, v151
	s_nop 0
	v_fma_f32 v48, -v54, v55, 1.0
	v_fmac_f32_e32 v55, v48, v55
	v_div_scale_f32 v48, vcc, 1.0, v153, 1.0
	v_mul_f32_e32 v49, v48, v55
	v_fma_f32 v50, -v54, v49, v48
	v_fmac_f32_e32 v49, v50, v55
	v_fma_f32 v48, -v54, v49, v48
	v_div_fmas_f32 v48, v48, v55, v49
	v_div_fixup_f32 v48, v48, v153, 1.0
	v_pk_mul_f32 v[44:45], v[48:49], v[44:45] op_sel_hi:[0,1]
	v_pk_mul_f32 v[50:51], v[44:45], s[18:19] op_sel_hi:[1,0]
	v_pk_mul_f32 v[46:47], v[48:49], v[46:47] op_sel_hi:[0,1]
	v_min_f32_e32 v49, 0x42700000, v50
	v_min_f32_e32 v51, 0x42700000, v51
	v_exp_f32_e32 v50, v49
	v_exp_f32_e32 v51, v51
	v_pk_mul_f32 v[42:43], v[48:49], v[42:43] op_sel_hi:[0,1]
	v_pk_mul_f32 v[40:41], v[48:49], v[40:41] op_sel_hi:[0,1]
	v_pk_mul_f32 v[36:37], v[48:49], v[36:37] op_sel_hi:[0,1]
	v_pk_add_f32 v[50:51], v[50:51], 1.0 op_sel_hi:[1,0]
	v_pk_mul_f32 v[36:37], v[36:37], v[44:45]
	v_mul_f32_e32 v49, v50, v51
	v_pk_mul_f32 v[38:39], v[48:49], v[38:39] op_sel_hi:[0,1]
	v_pk_mul_f32 v[38:39], v[38:39], v[46:47]
	v_pk_mul_f32 v[44:45], v[46:47], s[18:19] op_sel_hi:[1,0]
	v_pk_mul_f32 v[46:47], v[40:41], s[18:19] op_sel_hi:[1,0]
	v_min_f32_e32 v44, 0x42700000, v44
	v_min_f32_e32 v45, 0x42700000, v45
	v_min_f32_e32 v46, 0x42700000, v46
	v_min_f32_e32 v47, 0x42700000, v47
	v_rcp_f32_e32 v52, v49
	v_exp_f32_e32 v44, v44
	v_exp_f32_e32 v45, v45
	v_exp_f32_e32 v46, v46
	v_exp_f32_e32 v47, v47
	v_pk_mul_f32 v[32:33], v[48:49], v[32:33] op_sel_hi:[0,1]
	v_pk_mul_f32 v[34:35], v[48:49], v[34:35] op_sel_hi:[0,1]
	v_pk_mul_f32 v[48:49], v[50:51], v[52:53] op_sel:[1,0] op_sel_hi:[0,0]
	v_pk_add_f32 v[44:45], v[44:45], 1.0 op_sel_hi:[1,0]
	v_pk_add_f32 v[46:47], v[46:47], 1.0 op_sel_hi:[1,0]
	v_pk_mul_f32 v[36:37], v[36:37], v[48:49]
	v_mul_f32_e32 v48, v44, v45
	v_mul_f32_e32 v49, v46, v47
	v_pk_mul_f32 v[52:53], v[42:43], s[18:19] op_sel_hi:[1,0]
	v_rcp_f32_e32 v48, v48
	v_rcp_f32_e32 v50, v49
; __device__ __forceinline__ unsigned cvt_pk_bf16(float lo, float hi) { unsigned r; asm volatile("v_cvt_pk_bf16_f32 %0, %1, %2" : "=v"(r) : "v"(lo), "v"(hi)); return r; }
; __device__ __forceinline__ float ld_agent(const float* p) { return __hip_atomic_load(p, __ATOMIC_RELAXED, __HIP_MEMORY_SCOPE_AGENT); }
; __device__ __forceinline__ f32x2 silu_mul2(f32x2 g, f32x2 u) {
;     f32x2 x = g * (-1.4426950408889634f); x.x = fminf(x.x, 60.f); x.y = fminf(x.y, 60.f);
;     f32x2 e; e.x = __builtin_amdgcn_exp2f(x.x); e.y = __builtin_amdgcn_exp2f(x.y);
;     const f32x2 d = e + 1.0f; const float r = __builtin_amdgcn_rcpf(d.x * d.y);
;     const f32x2 sg = (f32x2){d.y, d.x} * r;
;     return (g * u) * sg;
; }
;     __device__ __forceinline__ void pre(const Unit& u, int wr, int fr, float (&r)[8]) const {
; #pragma unroll
;         for (int i = 0; i < 8; ++i) r[i] = rowss ? ld_agent(rowss + u.pm * BM + wr * 64 + fr + (i >> 2) * HALF + (i & 3) * 16) : 0.f; }
;     __device__ __forceinline__ void row(const f32x4 (&v)[2][2], const Unit& u, int row, int wc, int fq, float rq) const {
;         const int col0 = u.pn * 128 + wc * 32 + 8 * fq; const float rs = rowss ? 1.0f / sqrtf(rq * (1.0f / DM) + EPS) : 1.0f;
;         const f32x4 g0 = v[0][0] * rs, g1 = v[0][1] * rs, u0 = v[1][0] * rs, u1 = v[1][1] * rs;
;         const f32x2 a = silu_mul2((f32x2){g0[0], g0[1]}, (f32x2){u0[0], u0[1]}), b = silu_mul2((f32x2){g0[2], g0[3]}, (f32x2){u0[2], u0[3]});
;         const f32x2 c = silu_mul2((f32x2){g1[0], g1[1]}, (f32x2){u1[0], u1[1]}), d = silu_mul2((f32x2){g1[2], g1[3]}, (f32x2){u1[2], u1[3]});
;         u32x4 w; w.x = cvt_pk_bf16(a.x, a.y); w.y = cvt_pk_bf16(b.x, b.y); w.z = cvt_pk_bf16(c.x, c.y); w.w = cvt_pk_bf16(d.x, d.y);
;         *(u32x4*)(H + (size_t)row * DFF + col0) = w;
	v_min_f32_e32 v49, 0x42700000, v52
	v_min_f32_e32 v51, 0x42700000, v53
	v_exp_f32_e32 v52, v49
	v_exp_f32_e32 v53, v51
	v_pk_mul_f32 v[44:45], v[44:45], v[48:49] op_sel:[1,0] op_sel_hi:[0,0]
	v_pk_mul_f32 v[38:39], v[38:39], v[44:45]
	v_pk_mul_f32 v[44:45], v[46:47], v[50:51] op_sel:[1,0] op_sel_hi:[0,0]
	v_pk_add_f32 v[46:47], v[52:53], 1.0 op_sel_hi:[1,0]
	v_pk_mul_f32 v[32:33], v[32:33], v[40:41]
	v_mul_f32_e32 v48, v46, v47
	v_rcp_f32_e32 v48, v48
	v_pk_mul_f32 v[34:35], v[34:35], v[42:43]
	v_pk_mul_f32 v[40:41], v[32:33], v[44:45]
	v_pk_mul_f32 v[32:33], v[46:47], v[48:49] op_sel:[1,0] op_sel_hi:[0,0]
	v_pk_mul_f32 v[42:43], v[34:35], v[32:33]
	v_cvt_pk_bf16_f32 v32, v36, v37
	v_cvt_pk_bf16_f32 v33, v38, v39
	v_div_scale_f32 v38, s[4:5], v152, v152, 1.0
	v_rcp_f32_e32 v39, v38
	v_mad_i64_i32 v[36:37], s[4:5], v56, s54, v[112:113]
	v_lshl_add_u64 v[36:37], v[36:37], 0, v[114:115]
	v_cvt_pk_bf16_f32 v34, v40, v41
	v_cvt_pk_bf16_f32 v35, v42, v43
	global_store_dwordx4 v[36:37], v[32:35], off
	v_add_u32_e32 v40, 0xa0, v151
	s_nop 0
	v_fma_f32 v32, -v38, v39, 1.0
	v_fmac_f32_e32 v39, v32, v39
	v_div_scale_f32 v32, vcc, 1.0, v152, 1.0
	v_mul_f32_e32 v33, v32, v39
	v_fma_f32 v34, -v38, v33, v32
	v_fmac_f32_e32 v33, v34, v39
	v_fma_f32 v32, -v38, v33, v32
	v_div_fmas_f32 v32, v32, v39, v33
	v_div_fixup_f32 v32, v32, v152, 1.0
	v_pk_mul_f32 v[20:21], v[32:33], v[20:21] op_sel_hi:[0,1]
	v_pk_mul_f32 v[34:35], v[20:21], s[18:19] op_sel_hi:[1,0]
	v_pk_mul_f32 v[22:23], v[32:33], v[22:23] op_sel_hi:[0,1]
	v_min_f32_e32 v33, 0x42700000, v34
	v_min_f32_e32 v35, 0x42700000, v35
	v_exp_f32_e32 v34, v33
	v_exp_f32_e32 v35, v35
	v_pk_mul_f32 v[18:19], v[32:33], v[18:19] op_sel_hi:[0,1]
	v_pk_mul_f32 v[16:17], v[32:33], v[16:17] op_sel_hi:[0,1]
	v_pk_mul_f32 v[24:25], v[32:33], v[24:25] op_sel_hi:[0,1]
	v_pk_add_f32 v[34:35], v[34:35], 1.0 op_sel_hi:[1,0]
	v_pk_mul_f32 v[20:21], v[20:21], v[24:25]
	v_mul_f32_e32 v33, v34, v35
	v_pk_mul_f32 v[26:27], v[32:33], v[26:27] op_sel_hi:[0,1]
	v_pk_mul_f32 v[26:27], v[22:23], v[26:27]
	v_pk_mul_f32 v[22:23], v[22:23], s[18:19] op_sel_hi:[1,0]
	v_pk_mul_f32 v[24:25], v[16:17], s[18:19] op_sel_hi:[1,0]
	v_min_f32_e32 v22, 0x42700000, v22
	v_min_f32_e32 v23, 0x42700000, v23
	v_min_f32_e32 v24, 0x42700000, v24
	v_min_f32_e32 v25, 0x42700000, v25
	v_rcp_f32_e32 v36, v33
	v_exp_f32_e32 v22, v22
	v_exp_f32_e32 v23, v23
	v_exp_f32_e32 v24, v24
	v_exp_f32_e32 v25, v25
	v_pk_mul_f32 v[28:29], v[32:33], v[28:29] op_sel_hi:[0,1]
	v_pk_mul_f32 v[30:31], v[32:33], v[30:31] op_sel_hi:[0,1]
	v_pk_mul_f32 v[32:33], v[34:35], v[36:37] op_sel:[1,0] op_sel_hi:[0,0]
	v_pk_add_f32 v[22:23], v[22:23], 1.0 op_sel_hi:[1,0]
	v_pk_add_f32 v[24:25], v[24:25], 1.0 op_sel_hi:[1,0]
	v_pk_mul_f32 v[20:21], v[32:33], v[20:21]
	v_mul_f32_e32 v32, v22, v23
	v_mul_f32_e32 v33, v24, v25
	v_pk_mul_f32 v[36:37], v[18:19], s[18:19] op_sel_hi:[1,0]
	v_rcp_f32_e32 v32, v32
	v_rcp_f32_e32 v34, v33
	v_min_f32_e32 v33, 0x42700000, v36
	v_min_f32_e32 v35, 0x42700000, v37
	v_exp_f32_e32 v36, v33
	v_exp_f32_e32 v37, v35
	v_pk_mul_f32 v[22:23], v[22:23], v[32:33] op_sel:[1,0] op_sel_hi:[0,0]
	v_pk_mul_f32 v[22:23], v[22:23], v[26:27]
	v_pk_mul_f32 v[24:25], v[24:25], v[34:35] op_sel:[1,0] op_sel_hi:[0,0]
	v_pk_add_f32 v[26:27], v[36:37], 1.0 op_sel_hi:[1,0]
	v_pk_mul_f32 v[16:17], v[16:17], v[28:29]
	v_mul_f32_e32 v32, v26, v27
	v_rcp_f32_e32 v32, v32
	v_pk_mul_f32 v[18:19], v[18:19], v[30:31]
	v_pk_mul_f32 v[24:25], v[24:25], v[16:17]
	v_pk_mul_f32 v[16:17], v[26:27], v[32:33] op_sel:[1,0] op_sel_hi:[0,0]
	v_pk_mul_f32 v[26:27], v[16:17], v[18:19]
	v_cvt_pk_bf16_f32 v16, v20, v21
	v_cvt_pk_bf16_f32 v17, v22, v23
	v_div_scale_f32 v22, s[4:5], v150, v150, 1.0
	v_rcp_f32_e32 v23, v22
	v_mad_i64_i32 v[20:21], s[4:5], v40, s54, v[112:113]
	v_lshl_add_u64 v[20:21], v[20:21], 0, v[114:115]
	v_cvt_pk_bf16_f32 v18, v24, v25
	v_cvt_pk_bf16_f32 v19, v26, v27
	global_store_dwordx4 v[20:21], v[16:19], off
	s_nop 1
	v_fma_f32 v16, -v22, v23, 1.0
	v_fmac_f32_e32 v23, v16, v23
	v_div_scale_f32 v16, vcc, 1.0, v150, 1.0
	v_mul_f32_e32 v17, v16, v23
	v_fma_f32 v18, -v22, v17, v16
	v_fmac_f32_e32 v17, v18, v23
	v_fma_f32 v16, -v22, v17, v16
	v_div_fmas_f32 v16, v16, v23, v17
	v_div_fixup_f32 v16, v16, v150, 1.0
	v_pk_mul_f32 v[4:5], v[16:17], v[4:5] op_sel_hi:[0,1]
	v_pk_mul_f32 v[18:19], v[4:5], s[18:19] op_sel_hi:[1,0]
	v_pk_mul_f32 v[6:7], v[16:17], v[6:7] op_sel_hi:[0,1]
	v_min_f32_e32 v17, 0x42700000, v18
	v_min_f32_e32 v19, 0x42700000, v19
	v_exp_f32_e32 v18, v17
	v_exp_f32_e32 v19, v19
	v_pk_mul_f32 v[2:3], v[16:17], v[2:3] op_sel_hi:[0,1]
	v_pk_mul_f32 v[0:1], v[16:17], v[0:1] op_sel_hi:[0,1]
	v_pk_mul_f32 v[8:9], v[16:17], v[8:9] op_sel_hi:[0,1]
	v_pk_add_f32 v[18:19], v[18:19], 1.0 op_sel_hi:[1,0]
	v_pk_mul_f32 v[4:5], v[4:5], v[8:9]
	v_mul_f32_e32 v17, v18, v19
	v_pk_mul_f32 v[10:11], v[16:17], v[10:11] op_sel_hi:[0,1]
	v_pk_mul_f32 v[10:11], v[6:7], v[10:11]
	v_pk_mul_f32 v[6:7], v[6:7], s[18:19] op_sel_hi:[1,0]
	v_pk_mul_f32 v[8:9], v[0:1], s[18:19] op_sel_hi:[1,0]
	v_min_f32_e32 v6, 0x42700000, v6
	v_min_f32_e32 v7, 0x42700000, v7
	v_min_f32_e32 v8, 0x42700000, v8
	v_min_f32_e32 v9, 0x42700000, v9
	v_rcp_f32_e32 v20, v17
	v_exp_f32_e32 v6, v6
	v_exp_f32_e32 v7, v7
	v_exp_f32_e32 v8, v8
	v_exp_f32_e32 v9, v9
	v_pk_mul_f32 v[12:13], v[16:17], v[12:13] op_sel_hi:[0,1]
	v_pk_mul_f32 v[14:15], v[16:17], v[14:15] op_sel_hi:[0,1]
	v_pk_mul_f32 v[16:17], v[18:19], v[20:21] op_sel:[1,0] op_sel_hi:[0,0]
	v_pk_add_f32 v[6:7], v[6:7], 1.0 op_sel_hi:[1,0]
	v_pk_add_f32 v[8:9], v[8:9], 1.0 op_sel_hi:[1,0]
	v_pk_mul_f32 v[4:5], v[16:17], v[4:5]
	v_mul_f32_e32 v16, v6, v7
	v_mul_f32_e32 v17, v8, v9
	v_pk_mul_f32 v[20:21], v[2:3], s[18:19] op_sel_hi:[1,0]
	v_rcp_f32_e32 v16, v16
	v_rcp_f32_e32 v18, v17
	v_min_f32_e32 v17, 0x42700000, v20
	v_min_f32_e32 v19, 0x42700000, v21
	v_exp_f32_e32 v20, v17
	v_exp_f32_e32 v21, v19
	v_pk_mul_f32 v[6:7], v[6:7], v[16:17] op_sel:[1,0] op_sel_hi:[0,0]
	v_pk_mul_f32 v[6:7], v[6:7], v[10:11]
	v_pk_mul_f32 v[8:9], v[8:9], v[18:19] op_sel:[1,0] op_sel_hi:[0,0]
	v_pk_add_f32 v[10:11], v[20:21], 1.0 op_sel_hi:[1,0]
	v_pk_mul_f32 v[0:1], v[0:1], v[12:13]
	v_mul_f32_e32 v16, v10, v11
	v_rcp_f32_e32 v16, v16
	v_add_u32_e32 v22, 0xb0, v151
	v_pk_mul_f32 v[2:3], v[2:3], v[14:15]
	v_pk_mul_f32 v[8:9], v[8:9], v[0:1]
	v_pk_mul_f32 v[0:1], v[10:11], v[16:17] op_sel:[1,0] op_sel_hi:[0,0]
	v_pk_mul_f32 v[10:11], v[0:1], v[2:3]
	v_cvt_pk_bf16_f32 v0, v4, v5
	v_mad_i64_i32 v[4:5], s[4:5], v22, s54, v[112:113]
	v_lshl_add_u64 v[4:5], v[4:5], 0, v[114:115]
	s_andn2_b64 vcc, exec, s[24:25]
	s_mov_b64 s[4:5], -1
	v_cvt_pk_bf16_f32 v1, v6, v7
	v_cvt_pk_bf16_f32 v2, v8, v9
	v_cvt_pk_bf16_f32 v3, v10, v11
	global_store_dwordx4 v[4:5], v[0:3], off
	s_cbranch_vccnz .LBB0_1618
	s_andn2_b64 vcc, exec, s[8:9]
	s_cbranch_vccnz .LBB0_1617
	s_barrier
	s_branch .LBB0_1617

; __global__ void __launch_bounds__(512, 2) fox_fwd(Args args) {
	.amdhsa_kernel _Z7fox_fwd4Args
		.amdhsa_group_segment_fixed_size 0
		.amdhsa_private_segment_fixed_size 0
		.amdhsa_kernarg_size 448
		.amdhsa_user_sgpr_count 2
		.amdhsa_user_sgpr_dispatch_ptr 0
		.amdhsa_user_sgpr_queue_ptr 0
		.amdhsa_user_sgpr_kernarg_segment_ptr 1
		.amdhsa_user_sgpr_dispatch_id 0
		.amdhsa_user_sgpr_kernarg_preload_length 0
		.amdhsa_user_sgpr_kernarg_preload_offset 0
		.amdhsa_user_sgpr_private_segment_size 0
		.amdhsa_uses_dynamic_stack 0
		.amdhsa_enable_private_segment 0
		.amdhsa_system_sgpr_workgroup_id_x 1
		.amdhsa_system_sgpr_workgroup_id_y 0
		.amdhsa_system_sgpr_workgroup_id_z 0
		.amdhsa_system_sgpr_workgroup_info 0
		.amdhsa_system_vgpr_workitem_id 2
		.amdhsa_next_free_vgpr 251
		.amdhsa_next_free_sgpr 98
		.amdhsa_accum_offset 252
		.amdhsa_reserve_vcc 1
		.amdhsa_float_round_mode_32 0
		.amdhsa_float_round_mode_16_64 0
		.amdhsa_float_denorm_mode_32 3
		.amdhsa_float_denorm_mode_16_64 3
		.amdhsa_dx10_clamp 1
		.amdhsa_ieee_mode 1
		.amdhsa_fp16_overflow 0
		.amdhsa_tg_split 0
		.amdhsa_exception_fp_ieee_invalid_op 0
		.amdhsa_exception_fp_denorm_src 0
		.amdhsa_exception_fp_ieee_div_zero 0
		.amdhsa_exception_fp_ieee_overflow 0
		.amdhsa_exception_fp_ieee_underflow 0
		.amdhsa_exception_fp_ieee_inexact 0
		.amdhsa_exception_int_div_zero 0
	.end_amdhsa_kernel

; __global__ void __launch_bounds__(512, 2) fox_fwd(Args args) {
amdhsa.kernels:
  - .agpr_count:     0
    .args:
      - .offset:         0
        .size:           192
        .value_kind:     by_value
      - .offset:         192
        .size:           4
        .value_kind:     hidden_block_count_x
      - .offset:         196
        .size:           4
        .value_kind:     hidden_block_count_y
      - .offset:         200
        .size:           4
        .value_kind:     hidden_block_count_z
      - .offset:         204
        .size:           2
        .value_kind:     hidden_group_size_x
      - .offset:         206
        .size:           2
        .value_kind:     hidden_group_size_y
      - .offset:         208
        .size:           2
        .value_kind:     hidden_group_size_z
      - .offset:         210
        .size:           2
        .value_kind:     hidden_remainder_x
      - .offset:         212
        .size:           2
        .value_kind:     hidden_remainder_y
      - .offset:         214
        .size:           2
        .value_kind:     hidden_remainder_z
      - .offset:         232
        .size:           8
        .value_kind:     hidden_global_offset_x
      - .offset:         240
        .size:           8
        .value_kind:     hidden_global_offset_y
      - .offset:         248
        .size:           8
        .value_kind:     hidden_global_offset_z
      - .offset:         256
        .size:           2
        .value_kind:     hidden_grid_dims
      - .offset:         280
        .size:           8
        .value_kind:     hidden_multigrid_sync_arg
      - .offset:         312
        .size:           4
        .value_kind:     hidden_dynamic_lds_size
    .group_segment_fixed_size: 0
    .kernarg_segment_align: 8
    .kernarg_segment_size: 448
    .language:       OpenCL C
    .language_version:
      - 2
      - 0
    .max_flat_workgroup_size: 512
    .name:           _Z7fox_fwd4Args
    .private_segment_fixed_size: 0
    .sgpr_count:     104
    .sgpr_spill_count: 16
    .symbol:         _Z7fox_fwd4Args.kd
    .uniform_work_group_size: 1
    .uses_dynamic_stack: false
    .vgpr_count:     251
    .vgpr_spill_count: 0
    .wavefront_size: 64
